# norm2 gain/shift/scale loads hoisted; per-row kernel-argument pointer reloads hoisted out of the route and norm2 row loops
# speedup vs baseline: 1.0992x; 1.0040x over previous
; __device__ __forceinline__ int opaque_tid() { int t = threadIdx.x; asm volatile("" : "+v"(t)); return t; }
; #define layer launder_s(layer_)
; __device__ __forceinline__ void route_item(const Params& p, int tile, unsigned char* smem) {
;   const int layer = 1;
;   float* rw = (float*)smem;
;   int* te = (int*)(smem + 32768);
;   int tid = opaque_tid(), wave = tid >> 6, lane = tid & 63;
;   for (int e = tid; e < 8192; e += NT) rw[e] = p.in[38][e];
;   __syncthreads();
;   const float* MOD = (const float*)(p.ws + O_MOD);
;   const float* g = p.in[7] + layer * D;
;   u16* XN = (u16*)(p.ws + O_XN);
;   int2* TOKE = (int2*)(p.ws + O_ROUTE + R_TOKE);
;   float2* TOKW = (float2*)(p.ws + O_ROUTE + R_TOKW);
;   for (int i = 0; i < 8; i++) {
;     int rl = wave * 8 + i;
;     int row = tile * 64 + rl;
;     const float* src = (const float*)(p.ws + O_XRES) + (size_t)row * D;
.LBB0_1004:
	s_or_b64 exec, exec, s[8:9]
	s_waitcnt vmcnt(0)
	v_mov_b64_e32 v[0:1], s[6:7]
	s_waitcnt lgkmcnt(0)
	s_barrier
	global_load_dwordx2 v[18:19], v[0:1], off offset:336
	s_nop 0
	global_load_dwordx2 v[0:1], v[0:1], off offset:56
	v_cmp_lt_i32_e32 vcc, v236, v235
	v_and_b32_e32 v3, 63, v16
	v_ashrrev_i32_e32 v2, 3, v16
	v_cndmask_b32_e32 v4, v234, v236, vcc
	v_cmp_lt_i32_e32 vcc, v237, v235
	v_lshlrev_b32_e32 v17, 2, v4
	s_mov_b64 s[8:9], 0x1000
	v_cndmask_b32_e32 v4, v234, v237, vcc
	v_cmp_lt_i32_e32 vcc, v238, v235
	v_lshlrev_b32_e32 v48, 2, v4
	v_and_b32_e32 v5, -8, v2
	v_cndmask_b32_e32 v4, v234, v238, vcc
	v_cmp_lt_i32_e32 vcc, v239, v235
	v_lshlrev_b32_e32 v49, 2, v4
	v_lshlrev_b32_e32 v2, 2, v3
	v_cndmask_b32_e32 v4, v234, v239, vcc
	v_cmp_lt_i32_e32 vcc, v240, v235
	v_lshlrev_b32_e32 v50, 2, v4
	v_lshlrev_b32_e32 v160, 4, v3
	v_cndmask_b32_e32 v4, v234, v240, vcc
	v_cmp_lt_i32_e32 vcc, v241, v235
	v_lshlrev_b32_e32 v51, 2, v4
	v_or_b32_e32 v6, 0x200, v2
	v_cndmask_b32_e32 v4, v234, v241, vcc
	v_lshlrev_b32_e32 v52, 2, v4
	v_or_b32_e32 v4, 0x100, v2
	v_or_b32_e32 v8, 0x300, v2
	s_mov_b64 s[10:11], 0x4800000
	v_lshlrev_b32_e32 v7, 5, v4
	v_lshlrev_b32_e32 v9, 5, v6
	v_lshlrev_b32_e32 v10, 5, v8
	s_mov_b32 s28, 0
	v_lshl_add_u32 v53, v3, 7, 0
	v_add_u32_e32 v34, s4, v5
	v_lshlrev_b32_e32 v36, 2, v4
	v_add_u32_e32 v55, 0, v7
	v_lshlrev_b32_e32 v38, 2, v6
	v_add_u32_e32 v56, 0, v9
	v_lshlrev_b32_e32 v40, 2, v8
	v_add_u32_e32 v57, 0, v10
	s_waitcnt vmcnt(0) lgkmcnt(0)
	v_lshl_add_u64 v[0:1], v[0:1], 0, s[8:9]
	v_lshl_add_u64 v[24:25], v[0:1], 0, v[160:161]
	v_lshlrev_b32_e32 v160, 2, v4
	v_lshl_add_u64 v[26:27], v[0:1], 0, v[160:161]
	v_lshlrev_b32_e32 v160, 2, v6
	v_lshl_add_u64 v[28:29], v[0:1], 0, v[160:161]
	v_lshlrev_b32_e32 v160, 2, v8
	v_lshl_add_u64 v[30:31], v[0:1], 0, v[160:161]
	v_lshlrev_b32_e32 v160, 3, v3
	s_mov_b64 s[8:9], 0x6d8c000
	v_lshl_add_u64 v[0:1], v[18:19], 0, v[160:161]
	v_lshl_add_u64 v[20:21], v[18:19], 0, s[8:9]
	s_mov_b64 s[8:9], 0x6dac000
	v_lshl_add_u64 v[32:33], v[0:1], 0, s[10:11]
	v_and_b32_e32 v0, 0xffffffc0, v16
	s_add_i32 s10, 0, 0x8000
	v_lshl_add_u64 v[22:23], v[18:19], 0, s[8:9]
	v_cmp_eq_u32_e64 s[8:9], 0, v3
	v_add_u32_e32 v54, s10, v0
	v_lshlrev_b32_e32 v160, 2, v2
	v_mov_b64_e32 v[124:125], s[6:7]
	global_load_dwordx4 v[124:127], v[124:125], off offset:336
	s_waitcnt vmcnt(0)
	s_branch .LBB0_1006

; __device__ __forceinline__ unsigned pack2(float a, float b) { unsigned r; asm("v_cvt_pk_bf16_f32 %0, %1, %2" : "=v"(r) : "v"(a), "v"(b)); return r; }
; #define layer launder_s(layer_)
; __device__ __forceinline__ void route_item(const Params& p, int tile, unsigned char* smem) {
;     ...
;   for (int i = 0; i < 8; i++) {
;     int rl = wave * 8 + i;
;     int row = tile * 64 + rl;
;     const float* src = (const float*)(p.ws + O_XRES) + (size_t)row * D;
;     int m = row >> 11;
;     const float* md = MOD + (size_t)(layer * 9 + m) * 6144 + 3072;
;     float4 v[4];
;     float ss = 0.f;
; #pragma unroll
;     for (int q = 0; q < 4; q++) {
;       v[q] = *(const float4*)(src + q * 256 + lane * 4);
;       ss += v[q].x * v[q].x + v[q].y * v[q].y + v[q].z * v[q].z + v[q].w * v[q].w;
;       *(float4*)(p.out + (size_t)row * D + q * 256 + lane * 4) = v[q];
;     }
;     ss = wave_sum(ss);
;     float rstd = rsqrtf(ss * (1.0f / 1024.0f) + EPS);
;     float lg[8];
; #pragma unroll
;     for (int e = 0; e < 8; e++) lg[e] = 0.f;
; #pragma unroll
;     for (int q = 0; q < 4; q++) {
;       int cidx = q * 256 + lane * 4;
;       float4 gg = *(const float4*)(g + cidx);
;       float4 sh = *(const float4*)(md + cidx);
;       float4 sc = *(const float4*)(md + 1024 + cidx);
;       float o[4];
;       o[0] = v[q].x * rstd * gg.x * (1.f + sc.x) + sh.x;
;       o[1] = v[q].y * rstd * gg.y * (1.f + sc.y) + sh.y;
;       o[2] = v[q].z * rstd * gg.z * (1.f + sc.z) + sh.z;
;       o[3] = v[q].w * rstd * gg.w * (1.f + sc.w) + sh.w;
;       uint2 ob; ob.x = pack2(o[0], o[1]); ob.y = pack2(o[2], o[3]);
;       *(uint2*)(XN + (size_t)row * D + cidx) = ob;
; #pragma unroll
;       for (int u = 0; u < 4; u++) {
;         float4 r0 = *(const float4*)(rw + (cidx + u) * 8);
;         float4 r1 = *(const float4*)(rw + (cidx + u) * 8 + 4);
;         lg[0] += o[u] * r0.x; lg[1] += o[u] * r0.y; lg[2] += o[u] * r0.z; lg[3] += o[u] * r0.w;
;         lg[4] += o[u] * r1.x; lg[5] += o[u] * r1.y; lg[6] += o[u] * r1.z; lg[7] += o[u] * r1.w;
;       }
.LBB0_1006:
	v_mov_b64_e32 v[44:45], s[6:7]
	s_waitcnt lgkmcnt(0)
	v_mov_b32_e32 v0, v124
	v_mov_b32_e32 v1, v125
	v_mov_b32_e32 v2, v126
	v_mov_b32_e32 v3, v127
	v_ashrrev_i32_e32 v35, 31, v34
	v_lshlrev_b64 v[46:47], 12, v[34:35]
	v_ashrrev_i32_e32 v4, 11, v34
	v_add_u32_e32 v4, 9, v4
	v_mul_hi_i32_i24_e32 v5, 0x6000, v4
	v_mul_i32_i24_e32 v4, 0x6000, v4
	v_lshl_add_u64 v[42:43], v[18:19], 0, v[4:5]
	s_mov_b64 s[10:11], 0x6c03000
	s_waitcnt lgkmcnt(0)
	v_lshl_add_u64 v[0:1], v[0:1], 0, v[46:47]
	v_lshl_add_u64 v[0:1], v[0:1], 0, v[160:161]
	global_load_dwordx4 v[12:15], v[0:1], off
	global_load_dwordx4 v[8:11], v[0:1], off offset:1024
	global_load_dwordx4 v[68:71], v[0:1], off offset:2048
	global_load_dwordx4 v[72:75], v[0:1], off offset:3072
	v_lshl_add_u64 v[2:3], v[2:3], 0, v[46:47]
	v_lshl_add_u64 v[44:45], v[2:3], 0, v[160:161]
	s_waitcnt vmcnt(3)
	global_store_dwordx4 v[44:45], v[12:15], off
	s_waitcnt vmcnt(3)
	global_store_dwordx4 v[44:45], v[8:11], off offset:1024
	s_waitcnt vmcnt(3)
	global_store_dwordx4 v[44:45], v[68:71], off offset:2048
	s_waitcnt vmcnt(3)
	global_store_dwordx4 v[44:45], v[72:75], off offset:3072
	v_mov_b32_e32 v6, v13
	v_mov_b32_e32 v4, v12
	v_mov_b32_e32 v58, v15
	v_mov_b32_e32 v7, v9
	v_mov_b32_e32 v5, v8
	v_pk_mul_f32 v[6:7], v[6:7], v[6:7]
	v_pk_fma_f32 v[4:5], v[4:5], v[4:5], v[6:7]
	v_mov_b32_e32 v6, v14
	v_mov_b32_e32 v7, v10
	v_mov_b32_e32 v59, v11
	v_pk_fma_f32 v[4:5], v[6:7], v[6:7], v[4:5]
	v_pk_fma_f32 v[58:59], v[58:59], v[58:59], v[4:5]
	v_add_f32_e32 v37, v58, v59
	v_mov_b32_e32 v4, v68
	v_mov_b32_e32 v5, v69
	v_mov_b32_e32 v6, v70
	v_mov_b32_e32 v7, v71
	v_mov_b32_e32 v0, v72
	v_mov_b32_e32 v1, v73
	v_mov_b32_e32 v2, v74
	v_mov_b32_e32 v3, v75
	v_mov_b32_e32 v60, v5
	v_mov_b32_e32 v62, v7
	v_mov_b32_e32 v46, v4
	v_mov_b32_e32 v61, v1
	v_mov_b32_e32 v47, v0
	v_pk_mul_f32 v[60:61], v[60:61], v[60:61]
	v_mov_b32_e32 v63, v3
	v_pk_fma_f32 v[46:47], v[46:47], v[46:47], v[60:61]
	v_mov_b32_e32 v60, v6
	v_mov_b32_e32 v61, v2
	v_pk_fma_f32 v[46:47], v[60:61], v[60:61], v[46:47]
	v_pk_fma_f32 v[46:47], v[62:63], v[62:63], v[46:47]
	v_lshl_add_u64 v[44:45], v[42:43], 0, s[10:11]
	v_add_f32_e32 v37, v37, v46
	s_mov_b64 s[10:11], 0x6c04000
	v_add_f32_e32 v37, v37, v47
	v_lshl_add_u64 v[46:47], v[42:43], 0, s[10:11]
	v_lshl_add_u64 v[42:43], v[44:45], 0, v[160:161]
	global_load_dwordx4 v[68:71], v[42:43], off
	v_lshl_add_u64 v[42:43], v[46:47], 0, v[160:161]
	global_load_dwordx4 v[58:61], v[24:25], off
	global_load_dwordx4 v[62:65], v[42:43], off
	v_mov_b32_e32 v121, 0
	global_load_dwordx4 v[84:87], v[26:27], off
	v_mov_b32_e32 v120, v36
	v_lshl_add_u64 v[122:123], v[44:45], 0, v[120:121]
	global_load_dwordx4 v[88:91], v[122:123], off
	v_mov_b32_e32 v120, v36
	v_lshl_add_u64 v[122:123], v[46:47], 0, v[120:121]
	global_load_dwordx4 v[92:95], v[122:123], off
	global_load_dwordx4 v[96:99], v[28:29], off
	v_mov_b32_e32 v120, v38
	v_lshl_add_u64 v[122:123], v[46:47], 0, v[120:121]
	global_load_dwordx4 v[100:103], v[122:123], off
	v_mov_b32_e32 v120, v38
	v_lshl_add_u64 v[122:123], v[44:45], 0, v[120:121]
	global_load_dwordx4 v[104:107], v[122:123], off
	global_load_dwordx4 v[108:111], v[30:31], off
	v_mov_b32_e32 v120, v40
	v_lshl_add_u64 v[122:123], v[44:45], 0, v[120:121]
	global_load_dwordx4 v[112:115], v[122:123], off
	v_mov_b32_e32 v120, v40
	v_lshl_add_u64 v[122:123], v[46:47], 0, v[120:121]
	global_load_dwordx4 v[116:119], v[122:123], off
	ds_bpermute_b32 v39, v17, v37
	s_waitcnt lgkmcnt(0)
	v_add_f32_e32 v37, v37, v39
	ds_bpermute_b32 v39, v48, v37
	s_waitcnt lgkmcnt(0)
	v_add_f32_e32 v37, v37, v39
	ds_bpermute_b32 v39, v49, v37
	s_waitcnt lgkmcnt(0)
	v_add_f32_e32 v37, v37, v39
	ds_bpermute_b32 v39, v50, v37
	s_waitcnt lgkmcnt(0)
	v_add_f32_e32 v37, v37, v39
	ds_bpermute_b32 v39, v51, v37
	s_waitcnt lgkmcnt(0)
	v_add_f32_e32 v37, v37, v39
	ds_bpermute_b32 v39, v52, v37
	s_waitcnt lgkmcnt(0)
	v_add_f32_e32 v37, v37, v39
	v_fmamk_f32 v37, v37, 0x3a800000, v229
	v_cmp_gt_f32_e32 vcc, s89, v37
	v_mul_f32_e32 v39, 0x4b800000, v37
	s_nop 0
	v_cndmask_b32_e32 v37, v37, v39, vcc
	v_rsq_f32_e32 v37, v37
	s_nop 0
	v_mul_f32_e32 v39, 0x45800000, v37
	v_cndmask_b32_e32 v66, v37, v39, vcc
	v_mul_f32_e32 v12, v12, v66
	v_mul_f32_e32 v8, v8, v66
	v_mul_f32_e32 v4, v4, v66
	v_mul_f32_e32 v0, v0, v66
	s_waitcnt vmcnt(0)
	v_mul_f32_e32 v12, v58, v12
	v_add_f32_e32 v37, 1.0, v62
	v_fma_f32 v37, v37, v12, v68
	v_mul_f32_e32 v12, v13, v66
	v_mul_f32_e32 v12, v59, v12
	v_add_f32_e32 v13, 1.0, v63
	v_fma_f32 v39, v13, v12, v69
	v_mul_f32_e32 v12, v14, v66
	v_mul_f32_e32 v12, v60, v12
	v_add_f32_e32 v13, 1.0, v64
	v_fma_f32 v41, v12, v13, v70
	v_mul_f32_e32 v12, v15, v66
	v_lshlrev_b64 v[14:15], 11, v[34:35]
	v_mul_f32_e32 v12, v61, v12
	v_add_f32_e32 v13, 1.0, v65
	v_lshl_add_u64 v[42:43], v[32:33], 0, v[14:15]
	v_fmac_f32_e32 v71, v12, v13
	v_cvt_pk_bf16_f32 v12, v37, v39
	v_cvt_pk_bf16_f32 v13, v41, v71
	global_store_dwordx2 v[42:43], v[12:13], off
	ds_read_b128 v[12:15], v53
	ds_read_b128 v[72:75], v53 offset:16
	ds_read_b128 v[76:79], v53 offset:32
	ds_read_b128 v[80:83], v53 offset:48
	s_waitcnt lgkmcnt(0)
	v_fma_f32 v65, v37, v12, 0
	v_fma_f32 v64, v37, v13, 0
	v_fma_f32 v63, v37, v14, 0
	v_fma_f32 v62, v37, v15, 0
	v_fma_f32 v61, v37, v72, 0
	v_fma_f32 v60, v37, v73, 0
	v_fma_f32 v59, v37, v74, 0
	v_fma_f32 v58, v37, v75, 0
	ds_read_b128 v[12:15], v53 offset:64
	ds_read_b128 v[72:75], v53 offset:80
	v_fmac_f32_e32 v65, v39, v76
	v_fmac_f32_e32 v64, v39, v77
	v_fmac_f32_e32 v63, v39, v78
	v_fmac_f32_e32 v62, v39, v79
	v_fmac_f32_e32 v61, v39, v80
	v_fmac_f32_e32 v60, v39, v81
	v_fmac_f32_e32 v59, v39, v82
	v_fmac_f32_e32 v58, v39, v83
	s_waitcnt lgkmcnt(0)
; __device__ __forceinline__ unsigned pack2(float a, float b) { unsigned r; asm("v_cvt_pk_bf16_f32 %0, %1, %2" : "=v"(r) : "v"(a), "v"(b)); return r; }
; __device__ __forceinline__ void route_item(const Params& p, int tile, unsigned char* smem) {
;     ...
;     for (int q = 0; q < 4; q++) {
;       int cidx = q * 256 + lane * 4;
;       float4 gg = *(const float4*)(g + cidx);
;       float4 sh = *(const float4*)(md + cidx);
;       float4 sc = *(const float4*)(md + 1024 + cidx);
;       float o[4];
;       o[0] = v[q].x * rstd * gg.x * (1.f + sc.x) + sh.x;
;       o[1] = v[q].y * rstd * gg.y * (1.f + sc.y) + sh.y;
;       o[2] = v[q].z * rstd * gg.z * (1.f + sc.z) + sh.z;
;       o[3] = v[q].w * rstd * gg.w * (1.f + sc.w) + sh.w;
;       uint2 ob; ob.x = pack2(o[0], o[1]); ob.y = pack2(o[2], o[3]);
;       *(uint2*)(XN + (size_t)row * D + cidx) = ob;
; #pragma unroll
;       for (int u = 0; u < 4; u++) {
;         float4 r0 = *(const float4*)(rw + (cidx + u) * 8);
;         float4 r1 = *(const float4*)(rw + (cidx + u) * 8 + 4);
;         lg[0] += o[u] * r0.x; lg[1] += o[u] * r0.y; lg[2] += o[u] * r0.z; lg[3] += o[u] * r0.w;
;         lg[4] += o[u] * r1.x; lg[5] += o[u] * r1.y; lg[6] += o[u] * r1.z; lg[7] += o[u] * r1.w;
;       }
	v_fmac_f32_e32 v65, v41, v12
	v_fmac_f32_e32 v64, v41, v13
	v_fmac_f32_e32 v63, v41, v14
	v_fmac_f32_e32 v62, v41, v15
	v_fmac_f32_e32 v61, v41, v72
	v_fmac_f32_e32 v60, v41, v73
	v_fmac_f32_e32 v59, v41, v74
	v_fmac_f32_e32 v58, v41, v75
	ds_read_b128 v[12:15], v53 offset:96
	ds_read_b128 v[72:75], v53 offset:112
	v_mov_b32_e32 v37, v161
	v_lshl_add_u64 v[68:69], v[44:45], 0, v[36:37]
	s_waitcnt lgkmcnt(0)
	v_fmac_f32_e32 v65, v71, v12
	v_fmac_f32_e32 v61, v71, v72
	v_fmac_f32_e32 v60, v71, v73
	v_lshl_add_u64 v[72:73], v[46:47], 0, v[36:37]
	v_fmac_f32_e32 v64, v71, v13
	v_fmac_f32_e32 v63, v71, v14
	v_fmac_f32_e32 v62, v71, v15
	v_fmac_f32_e32 v59, v71, v74
	v_fmac_f32_e32 v58, v71, v75
	v_mov_b32_e32 v12, v84
	v_mov_b32_e32 v13, v85
	v_mov_b32_e32 v14, v86
	v_mov_b32_e32 v15, v87
	s_waitcnt lgkmcnt(0)
	v_mul_f32_e32 v8, v8, v12
	v_mov_b32_e32 v68, v88
	v_mov_b32_e32 v69, v89
	v_mov_b32_e32 v70, v90
	v_mov_b32_e32 v71, v91
	s_nop 0
	v_mov_b32_e32 v72, v92
	v_mov_b32_e32 v73, v93
	v_mov_b32_e32 v74, v94
	v_mov_b32_e32 v75, v95
	s_waitcnt lgkmcnt(0)
	v_add_f32_e32 v12, 1.0, v72
	v_fma_f32 v37, v8, v12, v68
	v_mul_f32_e32 v8, v9, v66
	v_mul_f32_e32 v8, v8, v13
	v_add_f32_e32 v9, 1.0, v73
	v_fma_f32 v39, v8, v9, v69
	v_mul_f32_e32 v8, v10, v66
	v_mul_f32_e32 v8, v8, v14
	v_add_f32_e32 v9, 1.0, v74
	v_fma_f32 v41, v8, v9, v70
	v_mul_f32_e32 v8, v11, v66
	v_mul_f32_e32 v8, v8, v15
	v_add_f32_e32 v9, 1.0, v75
	v_fmac_f32_e32 v71, v8, v9
	v_cvt_pk_bf16_f32 v8, v37, v39
	v_cvt_pk_bf16_f32 v9, v41, v71
	global_store_dwordx2 v[42:43], v[8:9], off offset:512
	ds_read_b128 v[8:11], v55
	ds_read_b128 v[12:15], v55 offset:16
	s_waitcnt lgkmcnt(0)
	v_fmac_f32_e32 v65, v37, v8
	v_fmac_f32_e32 v64, v37, v9
	v_fmac_f32_e32 v63, v37, v10
	v_fmac_f32_e32 v62, v37, v11
	v_fmac_f32_e32 v61, v37, v12
	v_fmac_f32_e32 v60, v37, v13
	v_fmac_f32_e32 v59, v37, v14
	v_fmac_f32_e32 v58, v37, v15
	ds_read_b128 v[8:11], v53 offset:8224
	ds_read_b128 v[12:15], v53 offset:8240
	ds_read_b128 v[72:75], v53 offset:8256
	ds_read_b128 v[76:79], v53 offset:8272
	s_waitcnt lgkmcnt(0)
	v_fmac_f32_e32 v65, v39, v8
	v_fmac_f32_e32 v64, v39, v9
	v_fmac_f32_e32 v63, v39, v10
	v_fmac_f32_e32 v62, v39, v11
	v_fmac_f32_e32 v61, v39, v12
	v_fmac_f32_e32 v60, v39, v13
	v_fmac_f32_e32 v59, v39, v14
	v_fmac_f32_e32 v58, v39, v15
	ds_read_b128 v[8:11], v53 offset:8288
	ds_read_b128 v[12:15], v53 offset:8304
	v_mov_b32_e32 v39, v161
	v_fmac_f32_e32 v65, v41, v72
	v_fmac_f32_e32 v64, v41, v73
	v_fmac_f32_e32 v63, v41, v74
	v_fmac_f32_e32 v62, v41, v75
	v_fmac_f32_e32 v61, v41, v76
	v_fmac_f32_e32 v60, v41, v77
	v_fmac_f32_e32 v59, v41, v78
	v_fmac_f32_e32 v58, v41, v79
	v_lshl_add_u64 v[68:69], v[46:47], 0, v[38:39]
	s_waitcnt lgkmcnt(0)
	v_fmac_f32_e32 v65, v71, v8
	v_fmac_f32_e32 v64, v71, v9
	v_fmac_f32_e32 v63, v71, v10
	v_fmac_f32_e32 v62, v71, v11
	v_fmac_f32_e32 v61, v71, v12
	v_fmac_f32_e32 v60, v71, v13
	v_fmac_f32_e32 v59, v71, v14
	v_fmac_f32_e32 v58, v71, v15
	v_mov_b32_e32 v8, v96
	v_mov_b32_e32 v9, v97
	v_mov_b32_e32 v10, v98
	v_mov_b32_e32 v11, v99
	v_lshl_add_u64 v[12:13], v[44:45], 0, v[38:39]
	v_mov_b32_e32 v68, v100
	v_mov_b32_e32 v69, v101
	v_mov_b32_e32 v70, v102
	v_mov_b32_e32 v71, v103
	v_mov_b32_e32 v41, v161
	v_mov_b32_e32 v12, v104
	v_mov_b32_e32 v13, v105
	v_mov_b32_e32 v14, v106
	v_mov_b32_e32 v15, v107
	s_waitcnt lgkmcnt(0)
	v_mul_f32_e32 v4, v4, v8
	v_add_f32_e32 v8, 1.0, v68
	v_fma_f32 v12, v4, v8, v12
	v_mul_f32_e32 v4, v5, v66
	v_mul_f32_e32 v4, v4, v9
	v_add_f32_e32 v5, 1.0, v69
	v_fma_f32 v13, v4, v5, v13
	v_mul_f32_e32 v4, v6, v66
	v_mul_f32_e32 v4, v4, v10
	v_add_f32_e32 v5, 1.0, v70
	v_fma_f32 v14, v4, v5, v14
	v_mul_f32_e32 v4, v7, v66
	v_mul_f32_e32 v4, v4, v11
	v_add_f32_e32 v5, 1.0, v71
	v_fmac_f32_e32 v15, v4, v5
	v_cvt_pk_bf16_f32 v4, v12, v13
	v_cvt_pk_bf16_f32 v5, v14, v15
	global_store_dwordx2 v[42:43], v[4:5], off offset:1024
	ds_read_b128 v[4:7], v56
	ds_read_b128 v[8:11], v56 offset:16
	s_waitcnt lgkmcnt(0)
	v_fmac_f32_e32 v65, v12, v4
	v_fmac_f32_e32 v64, v12, v5
	v_fmac_f32_e32 v63, v12, v6
	v_fmac_f32_e32 v62, v12, v7
	v_fmac_f32_e32 v61, v12, v8
	v_fmac_f32_e32 v60, v12, v9
	v_fmac_f32_e32 v59, v12, v10
	v_fmac_f32_e32 v58, v12, v11
	ds_read_b128 v[4:7], v53 offset:16416
	ds_read_b128 v[8:11], v53 offset:16432
	ds_read_b128 v[68:71], v53 offset:16448
	ds_read_b128 v[72:75], v53 offset:16464
	s_waitcnt lgkmcnt(0)
	v_fmac_f32_e32 v65, v13, v4
	v_fmac_f32_e32 v64, v13, v5
	v_fmac_f32_e32 v63, v13, v6
	v_fmac_f32_e32 v62, v13, v7
	v_fmac_f32_e32 v61, v13, v8
	v_fmac_f32_e32 v60, v13, v9
	v_fmac_f32_e32 v59, v13, v10
	v_fmac_f32_e32 v58, v13, v11
	ds_read_b128 v[4:7], v53 offset:16480
	ds_read_b128 v[8:11], v53 offset:16496
	v_fmac_f32_e32 v61, v14, v72
	v_fmac_f32_e32 v60, v14, v73
	v_fmac_f32_e32 v65, v14, v68
	v_fmac_f32_e32 v64, v14, v69
	v_fmac_f32_e32 v63, v14, v70
	v_fmac_f32_e32 v62, v14, v71
	v_fmac_f32_e32 v59, v14, v74
	v_fmac_f32_e32 v58, v14, v75
	s_waitcnt lgkmcnt(0)
	v_fmac_f32_e32 v61, v15, v8
	v_fmac_f32_e32 v60, v15, v9
	v_lshl_add_u64 v[8:9], v[44:45], 0, v[40:41]
	v_lshl_add_u64 v[12:13], v[46:47], 0, v[40:41]
	v_fmac_f32_e32 v65, v15, v4
	v_fmac_f32_e32 v64, v15, v5
	v_fmac_f32_e32 v63, v15, v6
	v_fmac_f32_e32 v62, v15, v7
	v_fmac_f32_e32 v59, v15, v10
	v_fmac_f32_e32 v58, v15, v11
	v_mov_b32_e32 v4, v108
	v_mov_b32_e32 v5, v109
	v_mov_b32_e32 v6, v110
	v_mov_b32_e32 v7, v111
	s_waitcnt lgkmcnt(0)
	v_mul_f32_e32 v0, v0, v4
	v_mov_b32_e32 v8, v112
	v_mov_b32_e32 v9, v113
	v_mov_b32_e32 v10, v114
	v_mov_b32_e32 v11, v115
	s_nop 0
	v_mov_b32_e32 v12, v116
	v_mov_b32_e32 v13, v117
	v_mov_b32_e32 v14, v118
	v_mov_b32_e32 v15, v119
	s_waitcnt lgkmcnt(0)
; __device__ __forceinline__ unsigned pack2(float a, float b) { unsigned r; asm("v_cvt_pk_bf16_f32 %0, %1, %2" : "=v"(r) : "v"(a), "v"(b)); return r; }
; __device__ __forceinline__ void route_item(const Params& p, int tile, unsigned char* smem) {
;     ...
;     for (int q = 0; q < 4; q++) {
;       int cidx = q * 256 + lane * 4;
;       float4 gg = *(const float4*)(g + cidx);
;       float4 sh = *(const float4*)(md + cidx);
;       float4 sc = *(const float4*)(md + 1024 + cidx);
;       float o[4];
;       o[0] = v[q].x * rstd * gg.x * (1.f + sc.x) + sh.x;
;       o[1] = v[q].y * rstd * gg.y * (1.f + sc.y) + sh.y;
;       o[2] = v[q].z * rstd * gg.z * (1.f + sc.z) + sh.z;
;       o[3] = v[q].w * rstd * gg.w * (1.f + sc.w) + sh.w;
;       uint2 ob; ob.x = pack2(o[0], o[1]); ob.y = pack2(o[2], o[3]);
;       *(uint2*)(XN + (size_t)row * D + cidx) = ob;
; #pragma unroll
;       for (int u = 0; u < 4; u++) {
;         float4 r0 = *(const float4*)(rw + (cidx + u) * 8);
;         float4 r1 = *(const float4*)(rw + (cidx + u) * 8 + 4);
;         lg[0] += o[u] * r0.x; lg[1] += o[u] * r0.y; lg[2] += o[u] * r0.z; lg[3] += o[u] * r0.w;
;         lg[4] += o[u] * r1.x; lg[5] += o[u] * r1.y; lg[6] += o[u] * r1.z; lg[7] += o[u] * r1.w;
;       }
;     }
; #pragma unroll
;     for (int e = 0; e < 8; e++) lg[e] = wave_sum(lg[e]);
	v_add_f32_e32 v4, 1.0, v12
	v_fma_f32 v4, v0, v4, v8
	v_mul_f32_e32 v0, v1, v66
	v_mul_f32_e32 v0, v0, v5
	v_add_f32_e32 v1, 1.0, v13
	v_fma_f32 v0, v0, v1, v9
	v_mul_f32_e32 v1, v2, v66
	v_mul_f32_e32 v1, v1, v6
	v_add_f32_e32 v2, 1.0, v14
	v_fma_f32 v1, v1, v2, v10
	v_mul_f32_e32 v2, v3, v66
	v_mul_f32_e32 v2, v2, v7
	v_add_f32_e32 v3, 1.0, v15
	v_fmac_f32_e32 v11, v2, v3
	v_cvt_pk_bf16_f32 v2, v4, v0
	v_cvt_pk_bf16_f32 v3, v1, v11
	global_store_dwordx2 v[42:43], v[2:3], off offset:1536
	ds_read_b128 v[6:9], v57
	ds_read_b128 v[12:15], v57 offset:16
	s_waitcnt lgkmcnt(0)
	v_fmac_f32_e32 v65, v4, v6
	v_fmac_f32_e32 v64, v4, v7
	v_fmac_f32_e32 v63, v4, v8
	v_fmac_f32_e32 v62, v4, v9
	v_fmac_f32_e32 v61, v4, v12
	v_fmac_f32_e32 v60, v4, v13
	v_fmac_f32_e32 v59, v4, v14
	v_fmac_f32_e32 v58, v4, v15
	ds_read_b128 v[2:5], v53 offset:24608
	ds_read_b128 v[6:9], v53 offset:24624
	ds_read_b128 v[12:15], v53 offset:24640
	ds_read_b128 v[42:45], v53 offset:24656
	s_waitcnt lgkmcnt(0)
	v_fmac_f32_e32 v65, v0, v2
	v_fmac_f32_e32 v64, v0, v3
	v_fmac_f32_e32 v63, v0, v4
	v_fmac_f32_e32 v62, v0, v5
	v_fmac_f32_e32 v61, v0, v6
	v_fmac_f32_e32 v60, v0, v7
	v_fmac_f32_e32 v59, v0, v8
	v_fmac_f32_e32 v58, v0, v9
	v_fmac_f32_e32 v65, v1, v12
	v_fmac_f32_e32 v64, v1, v13
	v_fmac_f32_e32 v63, v1, v14
	v_fmac_f32_e32 v62, v1, v15
	v_fmac_f32_e32 v61, v1, v42
	v_fmac_f32_e32 v60, v1, v43
	v_fmac_f32_e32 v59, v1, v44
	v_fmac_f32_e32 v58, v1, v45
	ds_read_b128 v[0:3], v53 offset:24672
	ds_read_b128 v[4:7], v53 offset:24688
	s_waitcnt lgkmcnt(0)
	v_fmac_f32_e32 v65, v11, v0
	v_fmac_f32_e32 v64, v11, v1
	v_fmac_f32_e32 v63, v11, v2
	v_fmac_f32_e32 v62, v11, v3
	v_fmac_f32_e32 v61, v11, v4
	v_fmac_f32_e32 v60, v11, v5
	v_fmac_f32_e32 v59, v11, v6
	v_fmac_f32_e32 v58, v11, v7
	ds_bpermute_b32 v0, v17, v65
	ds_bpermute_b32 v2, v17, v64
	ds_bpermute_b32 v4, v17, v63
	ds_bpermute_b32 v6, v17, v62
	ds_bpermute_b32 v8, v17, v61
	ds_bpermute_b32 v10, v17, v60
	ds_bpermute_b32 v12, v17, v59
	ds_bpermute_b32 v14, v17, v58
	s_waitcnt lgkmcnt(0)
	v_add_f32_e32 v0, v65, v0
	v_add_f32_e32 v2, v64, v2
	v_add_f32_e32 v4, v63, v4
	v_add_f32_e32 v6, v62, v6
	v_add_f32_e32 v8, v61, v8
	v_add_f32_e32 v10, v60, v10
	v_add_f32_e32 v12, v59, v12
	v_add_f32_e32 v14, v58, v14
	ds_bpermute_b32 v1, v48, v0
	ds_bpermute_b32 v3, v48, v2
	ds_bpermute_b32 v5, v48, v4
	ds_bpermute_b32 v7, v48, v6
	ds_bpermute_b32 v9, v48, v8
	ds_bpermute_b32 v11, v48, v10
	ds_bpermute_b32 v13, v48, v12
	ds_bpermute_b32 v15, v48, v14
	s_waitcnt lgkmcnt(0)
	v_add_f32_e32 v0, v0, v1
	v_add_f32_e32 v2, v2, v3
	v_add_f32_e32 v4, v4, v5
	v_add_f32_e32 v6, v6, v7
	v_add_f32_e32 v8, v8, v9
	v_add_f32_e32 v10, v10, v11
	v_add_f32_e32 v12, v12, v13
	v_add_f32_e32 v14, v14, v15
	ds_bpermute_b32 v1, v49, v0
	ds_bpermute_b32 v3, v49, v2
	ds_bpermute_b32 v5, v49, v4
	ds_bpermute_b32 v7, v49, v6
	ds_bpermute_b32 v9, v49, v8
	ds_bpermute_b32 v11, v49, v10
	ds_bpermute_b32 v13, v49, v12
	ds_bpermute_b32 v15, v49, v14
	s_waitcnt lgkmcnt(0)
	v_add_f32_e32 v0, v0, v1
	v_add_f32_e32 v2, v2, v3
	v_add_f32_e32 v4, v4, v5
	v_add_f32_e32 v6, v6, v7
	v_add_f32_e32 v8, v8, v9
	v_add_f32_e32 v10, v10, v11
	v_add_f32_e32 v12, v12, v13
	v_add_f32_e32 v14, v14, v15
	ds_bpermute_b32 v1, v50, v0
	ds_bpermute_b32 v3, v50, v2
	ds_bpermute_b32 v5, v50, v4
	ds_bpermute_b32 v7, v50, v6
	ds_bpermute_b32 v9, v50, v8
	ds_bpermute_b32 v11, v50, v10
	ds_bpermute_b32 v13, v50, v12
	ds_bpermute_b32 v15, v50, v14
	s_waitcnt lgkmcnt(0)
	v_add_f32_e32 v0, v0, v1
	v_add_f32_e32 v2, v2, v3
	v_add_f32_e32 v4, v4, v5
	v_add_f32_e32 v6, v6, v7
	v_add_f32_e32 v8, v8, v9
	v_add_f32_e32 v10, v10, v11
	v_add_f32_e32 v12, v12, v13
	v_add_f32_e32 v14, v14, v15
	ds_bpermute_b32 v1, v51, v0
	ds_bpermute_b32 v3, v51, v2
	ds_bpermute_b32 v5, v51, v4
	ds_bpermute_b32 v7, v51, v6
	ds_bpermute_b32 v9, v51, v8
	ds_bpermute_b32 v11, v51, v10
	ds_bpermute_b32 v13, v51, v12
	ds_bpermute_b32 v15, v51, v14
	s_waitcnt lgkmcnt(0)
	v_add_f32_e32 v0, v0, v1
	v_add_f32_e32 v2, v2, v3
	v_add_f32_e32 v4, v4, v5
	v_add_f32_e32 v6, v6, v7
	v_add_f32_e32 v8, v8, v9
	v_add_f32_e32 v10, v10, v11
	v_add_f32_e32 v12, v12, v13
	v_add_f32_e32 v14, v14, v15
	ds_bpermute_b32 v1, v52, v0
	ds_bpermute_b32 v3, v52, v2
	ds_bpermute_b32 v5, v52, v4
	ds_bpermute_b32 v7, v52, v6
	ds_bpermute_b32 v9, v52, v8
	ds_bpermute_b32 v11, v52, v10
	ds_bpermute_b32 v13, v52, v12
	ds_bpermute_b32 v15, v52, v14
	s_and_saveexec_b64 s[26:27], s[8:9]
	s_cbranch_execz .LBB0_1005
; __device__ __forceinline__ void route_item(const Params& p, int tile, unsigned char* smem) {
;     ...
;     for (int e = 0; e < 8; e++) lg[e] = wave_sum(lg[e]);
;     float mx = lg[0];
; #pragma unroll
;     for (int e = 1; e < 8; e++) mx = fmaxf(mx, lg[e]);
;     float pr[8];
; #pragma unroll
;     for (int e = 0; e < 8; e++) pr[e] = expf(lg[e] - mx);
;     int e0 = 0; float p0 = pr[0];
; #pragma unroll
;     for (int e = 1; e < 8; e++) if (pr[e] > p0) { p0 = pr[e]; e0 = e; }
;     int e1 = -1; float p1 = -1.f;
; #pragma unroll
;     for (int e = 0; e < 8; e++) if (e != e0 && pr[e] > p1) { p1 = pr[e]; e1 = e; }
;     float inv = 1.0f / (p0 + p1);
;     if (lane == 0) {
;       TOKE[row] = make_int2(e0, e1);
;       TOKW[row] = make_float2(p0 * inv, p1 * inv);
;       te[rl * 2] = e0; te[rl * 2 + 1] = e1;
;     }
	s_waitcnt lgkmcnt(0)
	v_add_f32_e32 v0, v0, v1
	v_add_f32_e32 v1, v2, v3
	v_max_f32_e32 v2, v0, v1
	v_add_f32_e32 v3, v4, v5
	v_add_f32_e32 v4, v6, v7
	v_max3_f32 v2, v2, v3, v4
	v_add_f32_e32 v5, v8, v9
	v_add_f32_e32 v6, v10, v11
	v_add_f32_e32 v14, v14, v15
	v_max3_f32 v2, v2, v5, v6
	v_add_f32_e32 v7, v12, v13
	v_max3_f32 v2, v2, v7, v14
	v_sub_f32_e32 v8, v14, v2
	v_mul_f32_e32 v9, 0x3fb8aa3b, v8
	v_fma_f32 v10, v8, s55, -v9
	v_rndne_f32_e32 v11, v9
	v_fmac_f32_e32 v10, 0x32a5705f, v8
	v_sub_f32_e32 v9, v9, v11
	v_add_f32_e32 v9, v9, v10
	v_exp_f32_e32 v9, v9
	v_cvt_i32_f32_e32 v10, v11
	v_sub_f32_e32 v7, v7, v2
	v_cmp_ngt_f32_e32 vcc, s56, v8
	v_sub_f32_e32 v6, v6, v2
	v_ldexp_f32 v9, v9, v10
	v_mul_f32_e32 v10, 0x3fb8aa3b, v7
	v_fma_f32 v11, v7, s55, -v10
	v_rndne_f32_e32 v12, v10
	v_fmac_f32_e32 v11, 0x32a5705f, v7
	v_sub_f32_e32 v10, v10, v12
	v_add_f32_e32 v10, v10, v11
	v_exp_f32_e32 v10, v10
	v_cvt_i32_f32_e32 v11, v12
	v_cndmask_b32_e32 v9, 0, v9, vcc
	v_cmp_nlt_f32_e32 vcc, s54, v8
	v_sub_f32_e32 v5, v5, v2
	v_sub_f32_e32 v4, v4, v2
	v_cndmask_b32_e32 v8, v242, v9, vcc
	v_ldexp_f32 v9, v10, v11
	v_mul_f32_e32 v10, 0x3fb8aa3b, v6
	v_fma_f32 v11, v6, s55, -v10
	v_rndne_f32_e32 v12, v10
	v_fmac_f32_e32 v11, 0x32a5705f, v6
	v_sub_f32_e32 v10, v10, v12
	v_add_f32_e32 v10, v10, v11
	v_exp_f32_e32 v10, v10
	v_cvt_i32_f32_e32 v11, v12
	v_cmp_ngt_f32_e32 vcc, s56, v7
	v_sub_f32_e32 v3, v3, v2
	v_sub_f32_e32 v1, v1, v2
	v_cndmask_b32_e32 v9, 0, v9, vcc
	v_cmp_nlt_f32_e32 vcc, s54, v7
	v_sub_f32_e32 v0, v0, v2
	v_mul_f32_e32 v2, 0x3fb8aa3b, v0
	v_cndmask_b32_e32 v7, v242, v9, vcc
	v_ldexp_f32 v9, v10, v11
	v_mul_f32_e32 v10, 0x3fb8aa3b, v5
	v_fma_f32 v11, v5, s55, -v10
	v_rndne_f32_e32 v12, v10
	v_fmac_f32_e32 v11, 0x32a5705f, v5
	v_sub_f32_e32 v10, v10, v12
	v_add_f32_e32 v10, v10, v11
	v_exp_f32_e32 v10, v10
	v_cvt_i32_f32_e32 v11, v12
	v_cmp_ngt_f32_e32 vcc, s56, v6
	s_nop 1
	v_cndmask_b32_e32 v9, 0, v9, vcc
	v_cmp_nlt_f32_e32 vcc, s54, v6
	s_nop 1
	v_cndmask_b32_e32 v6, v242, v9, vcc
	v_ldexp_f32 v9, v10, v11
	v_mul_f32_e32 v10, 0x3fb8aa3b, v4
	v_fma_f32 v11, v4, s55, -v10
	v_rndne_f32_e32 v12, v10
	v_fmac_f32_e32 v11, 0x32a5705f, v4
	v_sub_f32_e32 v10, v10, v12
	v_add_f32_e32 v10, v10, v11
	v_exp_f32_e32 v10, v10
	v_cvt_i32_f32_e32 v11, v12
	v_cmp_ngt_f32_e32 vcc, s56, v5
	s_nop 1
	v_cndmask_b32_e32 v9, 0, v9, vcc
	v_cmp_nlt_f32_e32 vcc, s54, v5
	s_nop 1
	v_cndmask_b32_e32 v5, v242, v9, vcc
	v_ldexp_f32 v9, v10, v11
	v_mul_f32_e32 v10, 0x3fb8aa3b, v3
	v_fma_f32 v11, v3, s55, -v10
	v_rndne_f32_e32 v12, v10
	v_fmac_f32_e32 v11, 0x32a5705f, v3
	v_sub_f32_e32 v10, v10, v12
	v_add_f32_e32 v10, v10, v11
	v_exp_f32_e32 v10, v10
	v_cvt_i32_f32_e32 v11, v12
	v_cmp_ngt_f32_e32 vcc, s56, v4
	s_nop 1
	v_cndmask_b32_e32 v9, 0, v9, vcc
	v_cmp_nlt_f32_e32 vcc, s54, v4
	s_nop 1
	v_cndmask_b32_e32 v4, v242, v9, vcc
	v_ldexp_f32 v9, v10, v11
	v_mul_f32_e32 v10, 0x3fb8aa3b, v1
	v_fma_f32 v11, v1, s55, -v10
	v_rndne_f32_e32 v12, v10
	v_fmac_f32_e32 v11, 0x32a5705f, v1
	v_sub_f32_e32 v10, v10, v12
	v_add_f32_e32 v10, v10, v11
	v_exp_f32_e32 v10, v10
	v_cvt_i32_f32_e32 v11, v12
	v_cmp_ngt_f32_e32 vcc, s56, v3
	s_nop 1
	v_cndmask_b32_e32 v9, 0, v9, vcc
	v_cmp_nlt_f32_e32 vcc, s54, v3
	s_nop 1
	v_cndmask_b32_e32 v3, v242, v9, vcc
	v_ldexp_f32 v9, v10, v11
	v_fma_f32 v10, v0, s55, -v2
	v_rndne_f32_e32 v11, v2
	v_fmac_f32_e32 v10, 0x32a5705f, v0
	v_sub_f32_e32 v2, v2, v11
	v_add_f32_e32 v2, v2, v10
	v_exp_f32_e32 v2, v2
	v_cvt_i32_f32_e32 v10, v11
	v_cmp_ngt_f32_e32 vcc, s56, v1
	v_ldexp_f32 v2, v2, v10
	s_nop 0
	v_cndmask_b32_e32 v9, 0, v9, vcc
	v_cmp_nlt_f32_e32 vcc, s54, v1
	s_nop 1
	v_cndmask_b32_e32 v1, v242, v9, vcc
	v_cmp_ngt_f32_e32 vcc, s56, v0
	s_nop 1
	v_cndmask_b32_e32 v2, 0, v2, vcc
	v_cmp_nlt_f32_e32 vcc, s54, v0
	s_nop 1
	v_cndmask_b32_e32 v2, v242, v2, vcc
	v_cmp_gt_f32_e32 vcc, v1, v2
	v_cmp_nlt_f32_e64 s[22:23], -1.0, v2
	s_nop 0
	v_cndmask_b32_e32 v0, v2, v1, vcc
	v_cmp_gt_f32_e64 s[10:11], v3, v0
	s_nop 1
	v_cndmask_b32_e64 v0, v0, v3, s[10:11]
	v_cmp_gt_f32_e64 s[12:13], v4, v0
	s_nop 1
	v_cndmask_b32_e64 v0, v0, v4, s[12:13]
	v_cmp_gt_f32_e64 s[14:15], v5, v0
	s_nop 1
	v_cndmask_b32_e64 v0, v0, v5, s[14:15]
	v_cmp_gt_f32_e64 s[16:17], v6, v0
	s_nop 1
	v_cndmask_b32_e64 v0, v0, v6, s[16:17]
	v_cmp_gt_f32_e64 s[18:19], v7, v0
	s_nop 1
	v_cndmask_b32_e64 v9, v0, v7, s[18:19]
	v_cndmask_b32_e64 v0, 0, 1, vcc
	v_cndmask_b32_e64 v0, v0, 2, s[10:11]
	v_cndmask_b32_e64 v0, v0, 3, s[12:13]
	v_cndmask_b32_e64 v0, v0, 4, s[14:15]
	v_cndmask_b32_e64 v0, v0, 5, s[16:17]
	v_cndmask_b32_e64 v0, v0, 6, s[18:19]
	v_cmp_ngt_f32_e32 vcc, v8, v9
	s_and_b64 s[30:31], s[18:19], vcc
	s_nop 0
	v_cndmask_b32_e32 v0, 7, v0, vcc
	v_cmp_eq_u32_e64 s[20:21], 0, v0
	s_or_b64 s[34:35], s[22:23], s[20:21]
	v_cndmask_b32_e64 v2, v2, -1.0, s[34:35]
	v_cmp_ne_u32_e64 s[18:19], 1, v0
	v_cmp_gt_f32_e64 s[20:21], v1, v2
	s_and_b64 s[18:19], s[18:19], s[20:21]
	v_cndmask_b32_e64 v1, v2, v1, s[18:19]
	v_cmp_ne_u32_e64 s[16:17], 2, v0
	v_cmp_gt_f32_e64 s[20:21], v3, v1
	s_and_b64 s[16:17], s[16:17], s[20:21]
	v_cndmask_b32_e64 v1, v1, v3, s[16:17]
	v_cmp_ne_u32_e64 s[14:15], 3, v0
	v_cmp_gt_f32_e64 s[20:21], v4, v1
	s_and_b64 s[14:15], s[14:15], s[20:21]
	v_cndmask_b32_e64 v1, v1, v4, s[14:15]
	v_cmp_ne_u32_e64 s[12:13], 4, v0
	v_cmp_gt_f32_e64 s[20:21], v5, v1
	s_and_b64 s[12:13], s[12:13], s[20:21]
	v_cndmask_b32_e64 v1, v1, v5, s[12:13]
	v_cmp_ne_u32_e64 s[10:11], 5, v0
	v_cmp_gt_f32_e64 s[20:21], v6, v1
	s_and_b64 s[10:11], s[10:11], s[20:21]
	v_cndmask_b32_e64 v1, v1, v6, s[10:11]
	v_cmp_ngt_f32_e64 s[20:21], v7, v1
	s_or_b64 s[20:21], s[30:31], s[20:21]
	s_nop 0
	v_cndmask_b32_e64 v1, v7, v1, s[20:21]
	v_cmp_gt_f32_e64 s[22:23], v8, v1
	s_and_b64 s[22:23], vcc, s[22:23]
	v_cndmask_b32_e32 v7, v8, v9, vcc
	v_cndmask_b32_e64 v6, v1, v8, s[22:23]
	v_cndmask_b32_e64 v1, 0, -1, s[34:35]
	v_cndmask_b32_e64 v1, v1, 1, s[18:19]
	v_cndmask_b32_e64 v1, v1, 2, s[16:17]
	v_cndmask_b32_e64 v1, v1, 3, s[14:15]
	v_add_f32_e32 v2, v7, v6
	v_cndmask_b32_e64 v1, v1, 4, s[12:13]
	v_div_scale_f32 v3, s[12:13], v2, v2, 1.0
	v_rcp_f32_e32 v4, v3
	v_cndmask_b32_e64 v1, v1, 5, s[10:11]
	v_cndmask_b32_e64 v1, 6, v1, s[20:21]
	v_cndmask_b32_e64 v1, v1, 7, s[22:23]
	v_fma_f32 v5, -v3, v4, 1.0
	v_fmac_f32_e32 v4, v5, v4
	v_div_scale_f32 v5, vcc, 1.0, v2, 1.0
	v_mul_f32_e32 v8, v5, v4
	v_fma_f32 v9, -v3, v8, v5
	v_fmac_f32_e32 v8, v9, v4
	v_fma_f32 v3, -v3, v8, v5
	v_div_fmas_f32 v3, v3, v4, v8
	v_div_fixup_f32 v8, v3, v2, 1.0
	v_lshlrev_b64 v[2:3], 3, v[34:35]
	v_lshl_add_u64 v[4:5], v[20:21], 0, v[2:3]
	global_store_dwordx2 v[4:5], v[0:1], off
	v_mul_f32_e32 v4, v7, v8
	v_mul_f32_e32 v5, v6, v8
	v_lshl_add_u64 v[2:3], v[22:23], 0, v[2:3]
	global_store_dwordx2 v[2:3], v[4:5], off
	v_add_u32_e32 v2, s28, v54
	ds_write_b64 v2, v[0:1]
	s_branch .LBB0_1005

; __device__ __forceinline__ int opaque_tid() { int t = threadIdx.x; asm volatile("" : "+v"(t)); return t; }
; #define layer launder_s(layer_)
; __device__ __forceinline__ void norm_item(const Params& p, int layer, int which, int item) {
;   int tid = opaque_tid(), wave = tid >> 6, lane = tid & 63;
;   const float* MOD = (const float*)(p.ws + O_MOD);
;   const float* g = p.in[which == 0 ? 6 : 7] + layer * D;
;   u16* XN = (u16*)(p.ws + O_XN);
;   for (int i = 0; i < 9; i++) {
;     int row = item * 72 + wave * 9 + i;
;     const float* src = resid_src(p, layer, which, row);
;     int m = row < TL ? (row >> 11) : 8;
;     const float* md = MOD + (size_t)(layer * 9 + m) * 6144 + (which == 0 ? 0 : 3072);
;     float4 v[4];
;     float ss = 0.f;
; #pragma unroll
;     for (int q = 0; q < 4; q++) {
;       v[q] = *(const float4*)(src + q * 256 + lane * 4);
;       ss += v[q].x * v[q].x + v[q].y * v[q].y + v[q].z * v[q].z + v[q].w * v[q].w;
;     }
;     ss = wave_sum(ss);
;     float rstd = rsqrtf(ss * (1.0f / 1024.0f) + EPS);
; #pragma unroll
;     for (int q = 0; q < 4; q++) {
;       int cidx = q * 256 + lane * 4;
;       float4 gg = *(const float4*)(g + cidx);
;       float4 sh = *(const float4*)(md + cidx);
;       float4 sc = *(const float4*)(md + 1024 + cidx);
.LBB0_1330:
	s_mov_b64 s[6:7], s[50:51]
	s_mov_b32 s9, 0
	v_mov_b32_e32 v4, v228
	s_waitcnt vmcnt(0)
	v_mov_b64_e32 v[0:1], s[6:7]
	v_mov_b64_e32 v[2:3], s[6:7]
	global_load_dwordx2 v[0:1], v[0:1], off offset:336
	v_cmp_lt_i32_e32 vcc, v236, v235
	global_load_dwordx2 v[2:3], v[2:3], off offset:56
	v_ashrrev_i32_e32 v5, 6, v4
	v_cndmask_b32_e32 v6, v234, v236, vcc
	v_cmp_lt_i32_e32 vcc, v237, v235
	s_lshl_b32 s10, s9, 10
	v_lshlrev_b32_e32 v4, 2, v4
	v_lshlrev_b32_e32 v42, 2, v6
	v_cndmask_b32_e32 v6, v234, v237, vcc
	v_cmp_lt_i32_e32 vcc, v238, v235
	s_ashr_i32 s11, s10, 31
	v_and_b32_e32 v4, 0xfc, v4
	v_lshlrev_b32_e32 v43, 2, v6
	v_cndmask_b32_e32 v6, v234, v238, vcc
	v_cmp_lt_i32_e32 vcc, v239, v235
	v_lshlrev_b32_e32 v44, 2, v6
	v_lshlrev_b32_e32 v160, 2, v4
	v_cndmask_b32_e32 v6, v234, v239, vcc
	v_cmp_lt_i32_e32 vcc, v240, v235
	v_lshlrev_b32_e32 v45, 2, v6
	v_or_b32_e32 v8, 0x300, v4
	v_cndmask_b32_e32 v6, v234, v240, vcc
	v_cmp_lt_i32_e32 vcc, v241, v235
	v_lshlrev_b32_e32 v46, 2, v6
	s_mov_b32 s8, 0
	v_cndmask_b32_e32 v6, v234, v241, vcc
	v_lshlrev_b32_e32 v47, 2, v6
	v_or_b32_e32 v6, 0x200, v4
	s_mul_i32 s9, s9, 9
	v_lshlrev_b32_e32 v30, 2, v6
	v_lshlrev_b32_e32 v32, 2, v8
	s_movk_i32 s12, 0x6000
	s_mov_b64 s[14:15], 0x1000
	s_waitcnt vmcnt(0) lgkmcnt(0)
	v_lshl_add_u64 v[2:3], s[10:11], 2, v[2:3]
	s_mov_b64 s[10:11], 0x6c03000
	v_lshl_add_u64 v[22:23], v[2:3], 0, v[160:161]
	v_lshlrev_b32_e32 v160, 1, v4
	v_lshl_add_u64 v[20:21], v[0:1], 0, s[10:11]
	v_lshl_add_u64 v[0:1], v[0:1], 0, v[160:161]
	s_mov_b64 s[10:11], 0x4800000
	v_or_b32_e32 v2, 0x100, v4
	v_lshl_add_u64 v[24:25], v[0:1], 0, s[10:11]
	v_mov_b32_e32 v0, s4
	v_mad_u64_u32 v[26:27], s[10:11], v5, 9, v[0:1]
	v_lshlrev_b32_e32 v160, 2, v4
	v_lshlrev_b32_e32 v28, 2, v2
	v_mov_b64_e32 v[124:125], s[6:7]
	global_load_dwordx2 v[124:125], v[124:125], off offset:336
	s_waitcnt vmcnt(0)
.LBB0_1331:
	v_mov_b32_e32 v0, v124
	v_mov_b32_e32 v1, v125
	v_add_u32_e32 v16, s8, v26
	v_ashrrev_i32_e32 v17, 31, v16
	v_lshlrev_b64 v[2:3], 12, v[16:17]
	v_mov_b32_e32 v31, v161
	v_mov_b32_e32 v33, v161
	s_add_i32 s8, s8, 1
	s_cmp_lg_u32 s8, 9
	s_waitcnt lgkmcnt(0)
	v_lshl_add_u64 v[0:1], v[0:1], 0, v[2:3]
	v_lshl_add_u64 v[0:1], v[0:1], 0, v[160:161]
	global_load_dwordx4 v[12:15], v[0:1], off
	global_load_dwordx4 v[8:11], v[0:1], off offset:1024
	v_min_i32_e32 v2, 0x4000, v16
	v_ashrrev_i32_e32 v2, 11, v2
	v_add_u32_e32 v27, s9, v2
	v_lshlrev_b64 v[16:17], 11, v[16:17]
	s_waitcnt vmcnt(0) lgkmcnt(0)
	v_mov_b32_e32 v4, v13
	v_mov_b32_e32 v5, v9
	v_mov_b32_e32 v2, v12
	v_mov_b32_e32 v3, v8
	v_pk_mul_f32 v[4:5], v[4:5], v[4:5]
	s_nop 0
	v_pk_fma_f32 v[2:3], v[2:3], v[2:3], v[4:5]
	v_mov_b32_e32 v4, v14
	v_mov_b32_e32 v5, v10
	v_pk_fma_f32 v[2:3], v[4:5], v[4:5], v[2:3]
	v_mov_b32_e32 v4, v15
	v_mov_b32_e32 v5, v11
	v_pk_fma_f32 v[18:19], v[4:5], v[4:5], v[2:3]
	global_load_dwordx4 v[4:7], v[0:1], off offset:2048
	s_nop 0
	global_load_dwordx4 v[0:3], v[0:1], off offset:3072
	v_add_f32_e32 v18, v18, v19
	global_load_dwordx4 v[48:51], v[22:23], off
	s_waitcnt vmcnt(0) lgkmcnt(0)
	v_mov_b32_e32 v36, v5
	v_mov_b32_e32 v37, v1
	v_mov_b32_e32 v34, v4
	v_mov_b32_e32 v35, v0
	v_pk_mul_f32 v[36:37], v[36:37], v[36:37]
	s_nop 0
	v_pk_fma_f32 v[34:35], v[34:35], v[34:35], v[36:37]
	v_mov_b32_e32 v36, v6
	v_mov_b32_e32 v37, v2
	v_pk_fma_f32 v[34:35], v[36:37], v[36:37], v[34:35]
	v_mov_b32_e32 v36, v7
	v_mov_b32_e32 v37, v3
	v_pk_fma_f32 v[34:35], v[36:37], v[36:37], v[34:35]
	v_lshl_add_u64 v[36:37], v[24:25], 0, v[16:17]
	v_add_f32_e32 v18, v18, v34
	v_add_f32_e32 v29, v18, v35
	v_mad_i64_i32 v[18:19], s[10:11], v27, s12, v[20:21]
	v_lshl_add_u64 v[34:35], v[18:19], 0, s[14:15]
	v_lshl_add_u64 v[38:39], v[18:19], 0, v[160:161]
	v_lshl_add_u64 v[18:19], v[34:35], 0, v[160:161]
	global_load_dwordx4 v[56:59], v[18:19], off
	global_load_dwordx4 v[52:55], v[38:39], off
	v_mov_b32_e32 v121, 0
	global_load_dwordx4 v[84:87], v[22:23], off offset:1024
	global_load_dwordx4 v[88:91], v[38:39], off offset:1024
	v_mov_b32_e32 v120, v28
	v_lshl_add_u64 v[122:123], v[34:35], 0, v[120:121]
	global_load_dwordx4 v[92:95], v[122:123], off
	global_load_dwordx4 v[96:99], v[22:23], off offset:2048
	global_load_dwordx4 v[100:103], v[38:39], off offset:2048
	v_mov_b32_e32 v120, v30
	v_lshl_add_u64 v[122:123], v[34:35], 0, v[120:121]
	global_load_dwordx4 v[104:107], v[122:123], off
	global_load_dwordx4 v[108:111], v[22:23], off offset:3072
	global_load_dwordx4 v[112:115], v[38:39], off offset:3072
	v_mov_b32_e32 v120, v32
	v_lshl_add_u64 v[122:123], v[34:35], 0, v[120:121]
	global_load_dwordx4 v[116:119], v[122:123], off
	ds_bpermute_b32 v27, v42, v29
	s_waitcnt lgkmcnt(0)
; __device__ __forceinline__ unsigned pack2(float a, float b) { unsigned r; asm("v_cvt_pk_bf16_f32 %0, %1, %2" : "=v"(r) : "v"(a), "v"(b)); return r; }
; __device__ __forceinline__ void norm_item(const Params& p, int layer, int which, int item) {
;     ...
;     float ss = 0.f;
; #pragma unroll
;     for (int q = 0; q < 4; q++) {
;       v[q] = *(const float4*)(src + q * 256 + lane * 4);
;       ss += v[q].x * v[q].x + v[q].y * v[q].y + v[q].z * v[q].z + v[q].w * v[q].w;
;     }
;     ss = wave_sum(ss);
;     float rstd = rsqrtf(ss * (1.0f / 1024.0f) + EPS);
; #pragma unroll
;     for (int q = 0; q < 4; q++) {
;       int cidx = q * 256 + lane * 4;
;       float4 gg = *(const float4*)(g + cidx);
;       float4 sh = *(const float4*)(md + cidx);
;       float4 sc = *(const float4*)(md + 1024 + cidx);
;       float o0 = v[q].x * rstd * gg.x * (1.f + sc.x) + sh.x;
;       float o1 = v[q].y * rstd * gg.y * (1.f + sc.y) + sh.y;
;       float o2 = v[q].z * rstd * gg.z * (1.f + sc.z) + sh.z;
;       float o3 = v[q].w * rstd * gg.w * (1.f + sc.w) + sh.w;
;       uint2 o; o.x = pack2(o0, o1); o.y = pack2(o2, o3);
;       *(uint2*)(XN + (size_t)row * D + cidx) = o;
;     }
;   }
	v_add_f32_e32 v27, v29, v27
	ds_bpermute_b32 v29, v43, v27
	s_waitcnt lgkmcnt(0)
	v_add_f32_e32 v27, v27, v29
	ds_bpermute_b32 v29, v44, v27
	s_waitcnt lgkmcnt(0)
	v_add_f32_e32 v27, v27, v29
	ds_bpermute_b32 v29, v45, v27
	s_waitcnt lgkmcnt(0)
	v_add_f32_e32 v27, v27, v29
	ds_bpermute_b32 v29, v46, v27
	s_waitcnt lgkmcnt(0)
	v_add_f32_e32 v27, v27, v29
	ds_bpermute_b32 v29, v47, v27
	s_waitcnt lgkmcnt(0)
	v_add_f32_e32 v27, v27, v29
	v_fmamk_f32 v27, v27, 0x3a800000, v229
	v_cmp_gt_f32_e32 vcc, s89, v27
	v_mul_f32_e32 v29, 0x4b800000, v27
	s_waitcnt vmcnt(0)
	v_add_f32_e32 v18, 1.0, v56
	v_cndmask_b32_e32 v27, v27, v29, vcc
	v_rsq_f32_e32 v27, v27
	s_nop 0
	v_mul_f32_e32 v29, 0x45800000, v27
	v_cndmask_b32_e32 v27, v27, v29, vcc
	v_mul_f32_e32 v12, v12, v27
	v_mul_f32_e32 v12, v48, v12
	v_mul_f32_e32 v13, v13, v27
	v_fma_f32 v12, v18, v12, v52
	v_mul_f32_e32 v13, v49, v13
	v_add_f32_e32 v18, 1.0, v57
	v_mul_f32_e32 v14, v14, v27
	v_fma_f32 v13, v18, v13, v53
	v_mul_f32_e32 v14, v50, v14
	v_add_f32_e32 v18, 1.0, v58
	v_mul_f32_e32 v15, v15, v27
	v_fma_f32 v14, v18, v14, v54
	v_mul_f32_e32 v15, v51, v15
	v_add_f32_e32 v18, 1.0, v59
	v_mov_b32_e32 v29, v161
	v_fmac_f32_e32 v55, v15, v18
	v_cvt_pk_bf16_f32 v12, v12, v13
	v_cvt_pk_bf16_f32 v13, v14, v55
	global_store_dwordx2 v[36:37], v[12:13], off
	v_lshl_add_u64 v[40:41], v[34:35], 0, v[28:29]
	v_mov_b32_e32 v16, v84
	v_mov_b32_e32 v17, v85
	v_mov_b32_e32 v18, v86
	v_mov_b32_e32 v19, v87
	v_mov_b32_e32 v12, v88
	v_mov_b32_e32 v13, v89
	v_mov_b32_e32 v14, v90
	v_mov_b32_e32 v15, v91
	v_mov_b32_e32 v48, v92
	v_mov_b32_e32 v49, v93
	v_mov_b32_e32 v50, v94
	v_mov_b32_e32 v51, v95
	v_mul_f32_e32 v8, v8, v27
	v_mul_f32_e32 v9, v9, v27
	v_mul_f32_e32 v10, v10, v27
	v_mul_f32_e32 v11, v11, v27
	v_mul_f32_e32 v4, v4, v27
	v_mul_f32_e32 v5, v5, v27
	v_mul_f32_e32 v6, v6, v27
	v_mul_f32_e32 v7, v7, v27
	v_mul_f32_e32 v0, v0, v27
	v_mul_f32_e32 v1, v1, v27
	v_mul_f32_e32 v2, v2, v27
	v_mul_f32_e32 v3, v3, v27
	s_waitcnt lgkmcnt(0)
	v_mul_f32_e32 v8, v8, v16
	v_mul_f32_e32 v9, v9, v17
	v_add_f32_e32 v16, 1.0, v48
	v_fma_f32 v8, v8, v16, v12
	v_add_f32_e32 v12, 1.0, v49
	v_fma_f32 v9, v9, v12, v13
	v_mul_f32_e32 v10, v10, v18
	v_add_f32_e32 v12, 1.0, v50
	v_fma_f32 v10, v10, v12, v14
	v_mul_f32_e32 v11, v11, v19
	v_add_f32_e32 v12, 1.0, v51
	v_fmac_f32_e32 v15, v11, v12
	v_cvt_pk_bf16_f32 v8, v8, v9
	v_cvt_pk_bf16_f32 v9, v10, v15
	global_store_dwordx2 v[36:37], v[8:9], off offset:512
	v_lshl_add_u64 v[16:17], v[34:35], 0, v[30:31]
	v_mov_b32_e32 v8, v96
	v_mov_b32_e32 v9, v97
	v_mov_b32_e32 v10, v98
	v_mov_b32_e32 v11, v99
	v_mov_b32_e32 v12, v100
	v_mov_b32_e32 v13, v101
	v_mov_b32_e32 v14, v102
	v_mov_b32_e32 v15, v103
	s_waitcnt lgkmcnt(0)
	v_mul_f32_e32 v4, v4, v8
	v_mov_b32_e32 v16, v104
	v_mov_b32_e32 v17, v105
	v_mov_b32_e32 v18, v106
	v_mov_b32_e32 v19, v107
	v_mul_f32_e32 v5, v5, v9
	v_mul_f32_e32 v6, v6, v10
	v_mul_f32_e32 v7, v7, v11
	s_waitcnt lgkmcnt(0)
	v_add_f32_e32 v8, 1.0, v16
	v_fma_f32 v4, v4, v8, v12
	v_add_f32_e32 v8, 1.0, v17
	v_fma_f32 v5, v5, v8, v13
	v_add_f32_e32 v8, 1.0, v18
	v_fma_f32 v6, v6, v8, v14
	v_add_f32_e32 v8, 1.0, v19
	v_fmac_f32_e32 v15, v7, v8
	v_cvt_pk_bf16_f32 v4, v4, v5
	v_cvt_pk_bf16_f32 v5, v6, v15
	global_store_dwordx2 v[36:37], v[4:5], off offset:1024
	v_lshl_add_u64 v[12:13], v[34:35], 0, v[32:33]
	v_mov_b32_e32 v4, v108
	v_mov_b32_e32 v5, v109
	v_mov_b32_e32 v6, v110
	v_mov_b32_e32 v7, v111
	v_mov_b32_e32 v8, v112
	v_mov_b32_e32 v9, v113
	v_mov_b32_e32 v10, v114
	v_mov_b32_e32 v11, v115
	s_waitcnt lgkmcnt(0)
	v_mul_f32_e32 v0, v0, v4
	v_mov_b32_e32 v12, v116
	v_mov_b32_e32 v13, v117
	v_mov_b32_e32 v14, v118
	v_mov_b32_e32 v15, v119
	v_mul_f32_e32 v1, v1, v5
	v_mul_f32_e32 v2, v2, v6
	v_mul_f32_e32 v3, v3, v7
	s_waitcnt lgkmcnt(0)
	v_add_f32_e32 v4, 1.0, v12
	v_fma_f32 v0, v0, v4, v8
	v_add_f32_e32 v4, 1.0, v13
	v_fma_f32 v1, v1, v4, v9
	v_add_f32_e32 v4, 1.0, v14
	v_fma_f32 v2, v2, v4, v10
	v_add_f32_e32 v4, 1.0, v15
	v_fmac_f32_e32 v11, v3, v4
	v_cvt_pk_bf16_f32 v0, v0, v1
	v_cvt_pk_bf16_f32 v1, v2, v11
	global_store_dwordx2 v[36:37], v[0:1], off offset:1536
	s_cbranch_scc1 .LBB0_1331
	v_readlane_b32 s6, v254, 42
	s_add_i32 s5, s5, s6
	v_readlane_b32 s6, v254, 33
	s_add_i32 s4, s4, s6
	s_cmpk_gt_i32 s5, 0xff
	v_readlane_b32 s7, v254, 43
	s_cbranch_scc0 .LBB0_1330
